# stagger11
# speedup vs baseline: 1.0029x; 1.0008x over previous
; #define LAS __attribute__((address_space(3)))
; __device__ __forceinline__ void attn_passes(const Params& p, LAS unsigned char* lds) {
;     ...
;     const int tid = threadIdx.x, w = __builtin_amdgcn_readfirstlane(tid >> 6), lane = tid & 63, qi = lane & 15, g = lane >> 4;
;     const int G = gridDim.x;
;     const float sc2 = 0.08838834764831845f * 1.4426950408889634f;
;     const int srow = tid >> 4, spc = tid & 15;
;     const int sch = spc ^ (((srow & 3) << 2) | ((srow >> 2) & 3));
;     const int krow = 8 * (qi >> 2) + (qi & 3);
;     unsigned koff[8], qrd[4];
; #pragma unroll
;     for (int ks = 0; ks < 4; ++ks) { koff[ks] = v_off(krow, 4 * ks + g); koff[4 + ks] = v_off(krow + 4, 4 * ks + g); qrd[ks] = QBUF_OFF + v_off(16 * w + qi, 4 * ks + g); }
;     unsigned tra[2];
;     { const int q4 = (lane & 15) >> 2, p4 = lane & 3;
; #pragma unroll
;       for (int t = 0; t < 2; ++t) tra[t] = v_off(8 * g + 4 * t + q4, p4 >> 1) + 8u * (p4 & 1); }
;     LAS unsigned char* ldsw = lds + w * 1024;
.Lpq_skip:
	s_lshr_b32 s101, s8, 8
	v_lshrrev_b32_e32 v131, 4, v128
	v_lshlrev_b32_e32 v3, 2, v131
	v_and_b32_e32 v0, 12, v3
	v_bfe_u32 v1, v128, 6, 2
	s_lshr_b32 s9, s8, 6
	v_bitop3_b32 v0, v0, v171, v1 bitop3:0x36
	s_lshl_b32 s4, s9, 10
	v_lshlrev_b32_e32 v90, 4, v0
	v_mov_b32_e32 v91, 0
	s_add_i32 s55, s4, 0
	v_lshl_add_u64 v[0:1], s[42:43], 0, v[90:91]
	s_mov_b64 s[4:5], 0x15600000
	v_bfe_u32 v2, v128, 4, 2
	v_lshrrev_b32_e32 v4, 2, v171
	v_and_b32_e32 v5, 3, v128
	v_lshrrev_b32_e32 v8, 1, v171
	v_lshl_add_u64 v[94:95], v[0:1], 0, s[4:5]
	s_mov_b64 s[4:5], 0x19600000
	v_lshl_or_b32 v5, v4, 3, v5
	v_and_b32_e32 v7, 12, v130
	v_and_b32_e32 v8, 2, v8
	v_or_b32_e32 v12, 4, v2
	v_lshl_add_u64 v[96:97], v[0:1], 0, s[4:5]
	v_cvt_f32_u32_e32 v1, s37
	v_lshlrev_b32_e32 v6, 8, v5
	v_bitop3_b32 v13, v8, v12, v7 bitop3:0x36
	v_lshl_or_b32 v139, v13, 4, v6
	v_or_b32_e32 v13, 8, v2
	v_bitop3_b32 v14, v8, v13, v7 bitop3:0x36
	v_or_b32_e32 v5, 4, v5
	v_lshl_or_b32 v174, v14, 4, v6
	v_or_b32_e32 v14, 12, v2
	v_rcp_iflag_f32_e32 v1, v1
	v_lshlrev_b32_e32 v9, 8, v5
	v_bfe_u32 v5, v5, 2, 2
	v_bitop3_b32 v11, v8, v2, v7 bitop3:0x36
	v_bitop3_b32 v8, v8, v14, v7 bitop3:0x36
	v_or_b32_e32 v10, v7, v152
	v_lshl_or_b32 v135, v11, 4, v6
	v_bitop3_b32 v11, v5, v2, v7 bitop3:0x36
	v_bitop3_b32 v12, v5, v12, v7 bitop3:0x36
	v_bitop3_b32 v13, v5, v13, v7 bitop3:0x36
	v_lshl_or_b32 v176, v8, 4, v6
	v_bitop3_b32 v5, v5, v14, v7 bitop3:0x36
	v_lshlrev_b32_e32 v6, 3, v2
	v_lshl_or_b32 v137, v11, 4, v9
	v_bitop3_b32 v11, v7, v2, v152 bitop3:0x36
	v_lshl_or_b32 v141, v12, 4, v9
	v_bitop3_b32 v12, v2, v10, 4 bitop3:0x36
	v_lshl_or_b32 v175, v13, 4, v9
	v_bitop3_b32 v13, v2, v10, 8 bitop3:0x36
	v_lshl_or_b32 v177, v5, 4, v9
	v_bitop3_b32 v5, v2, v10, 12 bitop3:0x36
	v_bfe_u32 v7, v128, 1, 1
	v_and_b32_e32 v8, 12, v128
	v_or_b32_e32 v10, v6, v4
	v_and_b32_e32 v14, 2, v133
	s_mul_i32 s54, s37, 6
	s_lshl_b32 s10, s9, 12
	v_lshlrev_b32_e32 v10, 8, v10
	v_or3_b32 v14, v8, v14, v7
	v_mul_f32_e32 v1, 0x4f7ffffe, v1
	v_lshl_or_b32 v10, v14, 4, v10
	v_or_b32_e32 v14, 4, v6
	v_lshl_add_u64 v[92:93], s[6:7], 0, v[90:91]
	s_add_i32 s56, s55, 0x20000
	s_lshr_b32 s6, s8, 7
	s_max_i32 s57, s54, 1
	s_add_i32 s58, s55, 0x10000
	s_add_i32 s59, s55, 0x12000
	s_add_i32 s60, s55, 0x14000
	s_add_i32 s61, s55, 0x16000
	s_add_i32 s62, s55, 0x18000
	s_add_i32 s63, s55, 0x1a000
	s_add_i32 s64, s55, 0x1c000
	s_add_i32 s65, s55, 0x1e000
	s_add_i32 s66, s55, 0x22000
	s_add_i32 s67, s55, 0x24000
	s_add_i32 s68, s55, 0x26000
	s_add_i32 s10, s10, 0
	v_cvt_u32_f32_e32 v1, v1
	v_or_b32_e32 v4, v14, v4
	v_bfe_u32 v14, v14, 2, 2
	s_add_u32 s69, s42, 0x3d600000
	v_lshlrev_b32_e32 v4, 8, v4
	v_bitop3_b32 v7, v14, v7, v8 bitop3:0x36
	s_addc_u32 s70, s43, 0
	v_and_b32_e32 v9, 8, v172
	v_lshl_or_b32 v4, v7, 4, v4
	s_movk_i32 s7, 0x60
	s_movk_i32 s8, 0x80
	s_add_u32 s71, s42, 0x31600000
	v_bitop3_b32 v183, v10, s7, v9 bitop3:0x36
	v_bitop3_b32 v184, v10, s8, v9 bitop3:0x36
	v_bitop3_b32 v190, v4, s7, v9 bitop3:0x36
	v_bitop3_b32 v191, v4, s8, v9 bitop3:0x36
	s_addc_u32 s72, s43, 0
	s_sub_i32 s7, 0, s37
	v_readfirstlane_b32 s8, v1
	v_cmp_eq_u32_e64 s[4:5], 0, v2
	v_lshl_add_u32 v2, v171, 8, s10
	s_mul_i32 s7, s7, s8
	v_lshlrev_b32_e32 v11, 4, v11
	v_lshlrev_b32_e32 v12, 4, v12
	v_lshlrev_b32_e32 v13, 4, v13
	v_lshlrev_b32_e32 v5, 4, v5
	s_movk_i32 s11, 0xa0
	s_movk_i32 s12, 0xc0
	s_movk_i32 s13, 0xe0
	v_and_b32_e32 v0, 8, v3
	v_add_u32_e32 v3, 0x20000, v2
	v_and_b32_e32 v2, 16, v128
	s_mul_hi_u32 s7, s8, s7
	s_lshl_b32 s74, s6, 5
	s_mov_b32 s24, 2.0
	s_mov_b32 s26, 4.0
	s_mov_b32 s28, 0x40c00000
	v_or_b32_e32 v178, v10, v9
	v_or_b32_e32 v179, v4, v9
	s_mov_b32 s23, 0
	v_or_b32_e32 v180, 0xffffff80, v131
	v_bitop3_b32 v181, v10, 32, v9 bitop3:0x36
	v_bitop3_b32 v182, v10, 64, v9 bitop3:0x36
	v_bitop3_b32 v185, v10, s11, v9 bitop3:0x36
	v_bitop3_b32 v186, v10, s12, v9 bitop3:0x36
	v_bitop3_b32 v187, v10, s13, v9 bitop3:0x36
	v_bitop3_b32 v188, v4, 32, v9 bitop3:0x36
	v_bitop3_b32 v189, v4, 64, v9 bitop3:0x36
	v_bitop3_b32 v192, v4, s11, v9 bitop3:0x36
	v_bitop3_b32 v193, v4, s12, v9 bitop3:0x36
	v_bitop3_b32 v194, v4, s13, v9 bitop3:0x36
	s_add_i32 s73, s8, s7
	v_or_b32_e32 v195, s74, v6
	s_lshl_b32 s75, s6, 14
	v_lshl_or_b32 v196, s9, 4, v171
	s_add_i32 s76, s55, 0x2000
	s_add_i32 s77, s55, 0x4000
	s_add_i32 s78, s55, 0x6000
	s_add_i32 s79, s55, 0x8000
	s_add_i32 s80, s55, 0xa000
	s_add_i32 s81, s55, 0xc000
	s_add_i32 s82, s55, 0xe000
	s_mov_b32 s83, 0xc2fc0000
	v_lshlrev_b32_e32 v98, 1, v0
	s_mov_b32 s25, 0x40400000
	s_mov_b32 s27, 0x40a00000
	s_mov_b32 s29, 0x40e00000
	v_lshlrev_b32_e32 v100, 1, v2
	v_add_u32_e32 v197, v3, v5
	v_add_u32_e32 v198, v3, v13
	v_add_u32_e32 v199, v3, v12
	v_add_u32_e32 v200, v3, v11
	s_movk_i32 s84, 0x81
	s_mov_b32 s36, 0x3e0293ee
	v_mbcnt_hi_u32_b32 v201, -1, v129
	s_mov_b32 s85, 0xf149f2ca
	v_mov_b32_e32 v202, 0x42800000
	v_mov_b32_e32 v103, 0x3e0293ee
	v_mov_b32_e32 v203, 0xff61b1e6
	v_mov_b32_e32 v204, 0xf149f2ca
	s_mov_b32 s86, 0
	s_branch .LBB0_251

; __device__ __forceinline__ void attn_passes(const Params& p, LAS unsigned char* lds) {
;     ...
;             const int lq = Ls + 128 * n + 16 * w + qi;
;             const size_t tq = ((size_t)lq << lg) + rho;
;             bf16x8 qf[4];
; #pragma unroll
;             for (int ks = 0; ks < 4; ++ks) qf[ks] = *(const LAS bf16x8*)(lds + qrd[ks]);
;             f32x4 o[8];
; #pragma unroll
;             for (int c = 0; c < 8; ++c) o[c] = (f32x4){0.f, 0.f, 0.f, 0.f};
;             float m = -1e30f, lsum = 0.f;
; #pragma unroll
;             for (int j = 0; j < 5; ++j) {
;                 if (j >= 1) {
;                     if (n < 3) { DMA_CHUNK(4 * n + 7 + j); if (j == 1) DMA_Q(n + 1); }
;                     else if (has_nxt) { DMA_CHUNK_NXT(3 + j); if (j == 1) DMA_Q_NXT(); }
;                 }
;                 const int k = 4 * n + (w >> 1) + j;
;                 LAS unsigned char* kb = lds + (k & 7) * 16384; LAS unsigned char* vb = kb + 8192;
;                 const int lb = Ls - 128 + 32 * k;
;                 bf16x8 kf[8]; s16x4 t0[8], t1[8];
;                 { const unsigned kbo = (unsigned)(size_t)kb;
;                   const unsigned k0 = kbo + koff[0], k1 = kbo + koff[1], k2 = kbo + koff[2], k3 = kbo + koff[3], k4 = kbo + koff[4], k5 = kbo + koff[5], k6 = kbo + koff[6], k7 = kbo + koff[7];
;                   asm volatile("ds_read_b128 %0, %8\n\tds_read_b128 %1, %9\n\tds_read_b128 %2, %10\n\tds_read_b128 %3, %11\n\tds_read_b128 %4, %12\n\tds_read_b128 %5, %13\n\tds_read_b128 %6, %14\n\tds_read_b128 %7, %15"
;                                : "=&v"(kf[0]), "=&v"(kf[4]), "=&v"(kf[1]), "=&v"(kf[5]), "=&v"(kf[2]), "=&v"(kf[6]), "=&v"(kf[3]), "=&v"(kf[7])
;                                : "v"(k0), "v"(k4), "v"(k1), "v"(k5), "v"(k2), "v"(k6), "v"(k3), "v"(k7) : "memory"); }
;                 const unsigned vbo = (unsigned)(size_t)vb;
;     ...
;                 TR_BATCH(0);
;                 asm volatile("s_waitcnt lgkmcnt(8)" : "+v"(kf[0]), "+v"(kf[1]), "+v"(kf[2]), "+v"(kf[3]), "+v"(kf[4]), "+v"(kf[5]), "+v"(kf[6]), "+v"(kf[7]) :: "memory");
;                 f32x4 s1 = (f32x4){0.f, 0.f, 0.f, 0.f}, s2 = s1;
; #pragma unroll
;                 for (int ks = 0; ks < 4; ++ks) {
;                     s1 = __builtin_amdgcn_mfma_f32_16x16x32_bf16(kf[ks], qf[ks], s1, 0, 0, 0); s2 = __builtin_amdgcn_mfma_f32_16x16x32_bf16(kf[4 + ks], qf[ks], s2, 0, 0, 0); }
.LBB0_257:
	s_cmpk_lg_i32 s89, 0x180
	s_cselect_b64 s[10:11], -1, 0
	s_add_i32 s93, s75, s91
	s_add_i32 s6, s93, 0xfffd4000
	ds_read_b128 v[0:3], v197
	ds_read_b128 v[4:7], v198
	ds_read_b128 v[8:11], v199
	ds_read_b128 v[12:15], v200
	s_and_b32 s6, s6, 0x1c000
	s_add_i32 s6, s6, 0
	s_add_i32 s8, s6, 0x2000
	v_add_u32_e32 v48, s6, v135
	v_add_u32_e32 v49, s6, v139
	v_add_u32_e32 v50, s6, v174
	v_add_u32_e32 v51, s6, v176
	v_add_u32_e32 v52, s6, v137
	v_add_u32_e32 v53, s6, v141
	v_add_u32_e32 v54, s6, v175
	v_add_u32_e32 v55, s6, v177
	s_waitcnt lgkmcnt(0)
	ds_read_b128 v[16:19], v48
	ds_read_b128 v[32:35], v52
	ds_read_b128 v[20:23], v49
	ds_read_b128 v[36:39], v53
	ds_read_b128 v[24:27], v50
	ds_read_b128 v[40:43], v54
	ds_read_b128 v[28:31], v51
	ds_read_b128 v[44:47], v55
	v_add_u32_e32 v48, s8, v178
	v_add_u32_e32 v49, s8, v179
	v_add_u32_e32 v50, s8, v181
	v_add_u32_e32 v51, s8, v188
	v_add_u32_e32 v68, s8, v182
	v_add_u32_e32 v69, s8, v189
	v_add_u32_e32 v70, s8, v183
	v_add_u32_e32 v71, s8, v190
	ds_read_b64_tr_b16 v[64:65], v48
	ds_read_b64_tr_b16 v[66:67], v49
	ds_read_b64_tr_b16 v[60:61], v50
	ds_read_b64_tr_b16 v[62:63], v51
	ds_read_b64_tr_b16 v[56:57], v68
	ds_read_b64_tr_b16 v[58:59], v69
	ds_read_b64_tr_b16 v[52:53], v70
	ds_read_b64_tr_b16 v[54:55], v71
	s_waitcnt lgkmcnt(8)
	v_add_u32_e32 v90, s89, v206
	s_waitcnt lgkmcnt(0)
	v_mfma_f32_16x16x32_bf16 v[16:19], v[16:19], v[12:15], 0
	s_add_i32 s92, s90, s89
	s_add_i32 s6, s92, 0xffffff80
	v_xor_b32_e32 v158, 0x80000000, v111
	v_mfma_f32_16x16x32_bf16 v[16:19], v[20:23], v[8:11], v[16:19]
	s_cmp_gt_i32 s6, -1
	s_cselect_b64 s[6:7], -1, 0
	v_add_u32_e32 v48, s8, v187
	v_mfma_f32_16x16x32_bf16 v[16:19], v[24:27], v[4:7], v[16:19]
	v_add_u32_e32 v24, s89, v101
	v_sub_u32_e32 v208, v90, v24
	v_add_u32_e32 v24, 0x80, v208
	v_mfma_f32_16x16x32_bf16 v[16:19], v[28:31], v[0:3], v[16:19]
	v_cvt_f32_i32_e32 v102, v24
	v_cmp_gt_u32_e32 vcc, s84, v24
	s_and_b64 vcc, s[6:7], vcc
	v_mfma_f32_16x16x32_bf16 v[32:35], v[32:35], v[12:15], 0
	v_add_u32_e32 v49, s8, v194
	s_nop 2
	v_mov_b32_e32 v159, v16
	v_pk_mul_f32 v[24:25], v[158:159], v[102:103]
	v_mfma_f32_16x16x32_bf16 v[20:23], v[36:39], v[8:11], v[32:35]
	v_add_f32_e32 v16, v110, v24
	v_add_f32_e32 v16, v16, v25
	v_add_u32_e32 v102, s89, v99
	v_cndmask_b32_e32 v32, v203, v16, vcc
	v_add_u32_e32 v16, 0x7f, v208
	v_cmp_gt_u32_e32 vcc, s84, v16
	v_add_f32_e32 v16, v111, v24
	v_fmac_f32_e32 v16, 0x3e0293ee, v17
	s_and_b64 vcc, s[6:7], vcc
	v_mfma_f32_16x16x32_bf16 v[20:23], v[40:43], v[4:7], v[20:23]
	v_cndmask_b32_e32 v33, v203, v16, vcc
	v_add_u32_e32 v16, 0x7e, v208
	v_cmp_gt_u32_e32 vcc, s84, v16
	v_add_f32_e32 v16, v112, v24
	v_fmac_f32_e32 v16, 0x3e0293ee, v18
	s_and_b64 vcc, s[6:7], vcc
	v_cndmask_b32_e32 v34, v203, v16, vcc
	v_add_u32_e32 v16, 0x7d, v208
	v_mfma_f32_16x16x32_bf16 v[20:23], v[44:47], v[0:3], v[20:23]
	v_cmp_gt_u32_e32 vcc, s84, v16
	v_add_f32_e32 v16, v113, v24
	v_fmac_f32_e32 v16, 0x3e0293ee, v19
	s_and_b64 vcc, s[6:7], vcc
	v_cndmask_b32_e32 v35, v203, v16, vcc
	v_add_u32_e32 v16, 0x7c, v208
	v_cmp_gt_u32_e32 vcc, s84, v16
	v_add_f32_e32 v16, v114, v24
	v_fmac_f32_e32 v16, 0x3e0293ee, v20
	s_and_b64 vcc, s[6:7], vcc
	v_cndmask_b32_e32 v36, v203, v16, vcc
	v_add_u32_e32 v16, 0x7b, v208
	v_cmp_gt_u32_e32 vcc, s84, v16
	v_add_f32_e32 v16, v115, v24
	v_fmac_f32_e32 v16, 0x3e0293ee, v21
	s_and_b64 vcc, s[6:7], vcc
	v_cndmask_b32_e32 v37, v203, v16, vcc
	v_add_u32_e32 v16, 0x7a, v208
	v_cmp_gt_u32_e32 vcc, s84, v16
	v_add_f32_e32 v16, v116, v24
	v_fmac_f32_e32 v16, 0x3e0293ee, v22
	s_and_b64 vcc, s[6:7], vcc
	v_cndmask_b32_e32 v38, v203, v16, vcc
	v_add_u32_e32 v16, 0x79, v208
	v_cmp_gt_u32_e32 vcc, s84, v16
	v_add_f32_e32 v16, v117, v24
	v_fmac_f32_e32 v16, 0x3e0293ee, v23
	s_and_b64 vcc, s[6:7], vcc
	v_cndmask_b32_e32 v39, v203, v16, vcc
	v_max_f32_e32 v18, v38, v39
	v_max_f32_e32 v16, v32, v33
	v_max_f32_e32 v17, v34, v35
	v_max3_f32 v18, v36, v37, v18
	v_max3_f32 v16, v16, v17, v18
	v_add_u32_e32 v40, s8, v184
	v_add_u32_e32 v41, s8, v191
	v_mov_b32_e32 v17, v16
	v_add_u32_e32 v42, s8, v185
	v_add_u32_e32 v43, s8, v192
	v_add_u32_e32 v44, s8, v186
	v_add_u32_e32 v45, s8, v193
	v_permlane16_swap_b32_e32 v16, v17
	v_max_f32_e32 v16, v16, v17
	v_mov_b32_e32 v17, v16
	v_mov_b32_e32 v18, v16
	s_nop 1
	v_permlane32_swap_b32_e32 v17, v18
	v_max_f32_e32 v16, v17, v18
	v_cmp_lt_f32_e32 vcc, s85, v16
	s_cmp_eq_u64 vcc, 0
	v_max_f32_e32 v46, 0xf149f2ca, v16
	s_cselect_b64 vcc, -1, 0
	v_cndmask_b32_e32 v160, v46, v204, vcc
	v_sub_f32_e32 v32, v32, v160
	v_exp_f32_e32 v215, v32
	v_sub_f32_e32 v32, v33, v160
	v_sub_f32_e32 v16, 0xf149f2ca, v46
	v_exp_f32_e32 v159, v32
	v_sub_f32_e32 v32, v34, v160
	v_exp_f32_e32 v47, v16
	v_exp_f32_e32 v209, v32
	v_sub_f32_e32 v32, v35, v160
	v_exp_f32_e32 v211, v32
	v_sub_f32_e32 v32, v36, v160
	v_exp_f32_e32 v213, v32
	v_sub_f32_e32 v32, v37, v160
	v_exp_f32_e32 v210, v32
	v_sub_f32_e32 v32, v38, v160
	ds_read_b64_tr_b16 v[28:29], v40
	ds_read_b64_tr_b16 v[30:31], v41
	ds_read_b64_tr_b16 v[24:25], v42
	ds_read_b64_tr_b16 v[26:27], v43
	ds_read_b64_tr_b16 v[20:21], v44
	ds_read_b64_tr_b16 v[22:23], v45
	ds_read_b64_tr_b16 v[16:17], v48
	ds_read_b64_tr_b16 v[18:19], v49
	v_mul_f32_e32 v40, 0, v47
	v_exp_f32_e32 v212, v32
	v_sub_f32_e32 v32, v39, v160
	v_cndmask_b32_e64 v48, v40, 0, vcc
	v_exp_f32_e32 v214, v32
	v_cvt_pk_bf16_f32 v68, v215, v159
	v_cvt_pk_bf16_f32 v69, v209, v211
	v_cvt_pk_bf16_f32 v70, v213, v210
	v_cvt_pk_bf16_f32 v71, v212, v214
	s_waitcnt lgkmcnt(0)
	v_mov_b32_e32 v49, v48
	v_mov_b32_e32 v50, v48
	v_mov_b32_e32 v51, v48
	s_barrier
	s_cmp_eq_u32 s101, 0
	s_cbranch_scc1 .Lstg_0
	s_sleep 11
; __device__ __forceinline__ void attn_passes(const Params& p, LAS unsigned char* lds) {
;     ...
; #pragma unroll
;                 for (int c = 0; c < 8; ++c) {
;                     const bf16x8 va = (bf16x8){t0[c][0], t0[c][1], t0[c][2], t0[c][3], t1[c][0], t1[c][1], t1[c][2], t1[c][3]};
;                     o[c] = __builtin_amdgcn_mfma_f32_16x16x32_bf16(va, pb, o[c], 0, 0, 0); }
.Lstg_0:
	s_cmpk_eq_i32 s89, 0x180
	v_mfma_f32_16x16x32_bf16 v[44:47], v[64:67], v[68:71], v[48:51]
	v_mfma_f32_16x16x32_bf16 v[40:43], v[60:63], v[68:71], v[48:51]
	v_mfma_f32_16x16x32_bf16 v[36:39], v[56:59], v[68:71], v[48:51]
	v_mfma_f32_16x16x32_bf16 v[32:35], v[52:55], v[68:71], v[48:51]
	v_mfma_f32_16x16x32_bf16 v[28:31], v[28:31], v[68:71], v[48:51]
	v_mfma_f32_16x16x32_bf16 v[24:27], v[24:27], v[68:71], v[48:51]
	v_mfma_f32_16x16x32_bf16 v[20:23], v[20:23], v[68:71], v[48:51]
	v_mfma_f32_16x16x32_bf16 v[16:19], v[16:19], v[68:71], v[48:51]
	s_cbranch_scc1 .LBB0_259
	s_nop 1
	v_add_u32_e32 v50, 0x80, v102
	v_max_i32_e32 v50, 0, v50
	v_min_i32_e32 v50, s88, v50
	v_mov_b32_e32 v51, v91
	v_lshlrev_b64 v[50:51], s87, v[50:51]
	s_add_i32 s6, s91, 0xffff4000
	v_lshl_add_u64 v[50:51], v[50:51], 0, s[22:23]
	s_and_b32 s6, s6, 0x10000
	v_lshlrev_b64 v[50:51], 8, v[50:51]
	s_add_i32 s6, s55, s6
	v_add_u32_e32 v49, s89, v205
	v_lshl_add_u64 v[52:53], v[104:105], 0, v[50:51]
	s_mov_b32 m0, s6
	v_add_u32_e32 v54, 0x80, v49
	global_load_lds_dwordx4 v[52:53], off
	v_lshl_add_u64 v[50:51], v[106:107], 0, v[50:51]
	s_add_i32 m0, s6, 0x2000
	s_nop 0
	global_load_lds_dwordx4 v[50:51], off
	v_min_i32_e32 v50, s88, v54
	v_ashrrev_i32_e32 v51, 31, v50
	v_lshlrev_b64 v[50:51], s87, v[50:51]
	v_lshl_add_u64 v[50:51], v[50:51], 0, s[22:23]
	v_lshlrev_b64 v[50:51], 8, v[50:51]
	v_lshl_add_u64 v[50:51], v[108:109], 0, v[50:51]
	s_mov_b32 m0, s56
	s_mov_b64 s[6:7], -1
	global_load_lds_dwordx4 v[50:51], off
	v_add_u32_e32 v50, 0xa0, v49
	v_min_i32_e32 v50, s88, v50
	v_ashrrev_i32_e32 v51, 31, v50
	v_lshlrev_b64 v[50:51], s87, v[50:51]
	v_lshl_add_u64 v[50:51], v[50:51], 0, s[22:23]
	v_lshlrev_b64 v[50:51], 8, v[50:51]
	v_lshl_add_u64 v[50:51], v[108:109], 0, v[50:51]
	s_mov_b32 m0, s66
	s_nop 0
	global_load_lds_dwordx4 v[50:51], off
	v_add_u32_e32 v50, 0xc0, v49
	v_min_i32_e32 v50, s88, v50
	v_ashrrev_i32_e32 v51, 31, v50
	v_lshlrev_b64 v[50:51], s87, v[50:51]
	v_lshl_add_u64 v[50:51], v[50:51], 0, s[22:23]
	v_lshlrev_b64 v[50:51], 8, v[50:51]
	v_lshl_add_u64 v[50:51], v[108:109], 0, v[50:51]
	s_mov_b32 m0, s67
	v_add_u32_e32 v49, 0xe0, v49
	global_load_lds_dwordx4 v[50:51], off
	v_min_i32_e32 v50, s88, v49
	v_ashrrev_i32_e32 v51, 31, v50
	v_lshlrev_b64 v[50:51], s87, v[50:51]
	v_lshl_add_u64 v[50:51], v[50:51], 0, s[22:23]
	v_lshlrev_b64 v[50:51], 8, v[50:51]
	v_lshl_add_u64 v[50:51], v[108:109], 0, v[50:51]
	s_cbranch_execz .LBB0_260
	s_branch .LBB0_263

; #define AT_BAR() do { asm volatile("" ::: "memory"); __builtin_amdgcn_s_barrier(); asm volatile("" ::: "memory"); } while (0)
; __device__ __forceinline__ void attn_passes(const Params& p, LAS unsigned char* lds) {
;     ...
;                 AT_BAR();
.LBB0_275:
	s_barrier
	s_cmp_eq_u32 s101, 0
	s_cbranch_scc1 .Lstg_1
	s_sleep 11
.Lstg_1:
	v_cndmask_b32_e64 v48, 0, 1, s[10:11]
	v_cmp_ne_u32_e64 s[6:7], 1, v48
	s_andn2_b64 vcc, exec, s[10:11]
	s_mov_b64 s[10:11], -1
	s_cbranch_vccnz .LBB0_277
	v_add_u32_e32 v48, 0xa0, v102
	v_max_i32_e32 v48, 0, v48
	v_min_i32_e32 v48, s88, v48
	v_mov_b32_e32 v49, v91
	v_lshlrev_b64 v[48:49], s87, v[48:49]
	s_add_i32 s10, s91, 0xffff8000
	v_lshl_add_u64 v[48:49], v[48:49], 0, s[22:23]
	s_and_b32 s10, s10, 0x14000
	v_lshlrev_b64 v[48:49], 8, v[48:49]
	s_add_i32 s10, s55, s10
	v_lshl_add_u64 v[50:51], v[104:105], 0, v[48:49]
	s_mov_b32 m0, s10
	v_lshl_add_u64 v[48:49], v[106:107], 0, v[48:49]
	global_load_lds_dwordx4 v[50:51], off
	s_add_i32 m0, s10, 0x2000
	s_mov_b64 s[10:11], 0
	global_load_lds_dwordx4 v[48:49], off

.Lstg_2:
	s_and_b64 vcc, exec, s[6:7]
	s_mov_b64 s[52:53], -1
	s_cbranch_vccnz .LBB0_292
	v_add_u32_e32 v48, 0xc0, v102
	v_max_i32_e32 v48, 0, v48
	v_min_i32_e32 v48, s88, v48
	v_mov_b32_e32 v49, v91
	v_lshlrev_b64 v[48:49], s87, v[48:49]
	s_add_i32 s52, s91, 0xffffc000
	v_lshl_add_u64 v[48:49], v[48:49], 0, s[22:23]
	s_and_b32 s52, s52, 0x18000
	v_lshlrev_b64 v[48:49], 8, v[48:49]
	s_add_i32 s52, s55, s52
	v_lshl_add_u64 v[50:51], v[104:105], 0, v[48:49]
	s_mov_b32 m0, s52
	v_lshl_add_u64 v[48:49], v[106:107], 0, v[48:49]
	global_load_lds_dwordx4 v[50:51], off
	s_add_i32 m0, s52, 0x2000
	s_mov_b64 s[52:53], 0
	global_load_lds_dwordx4 v[48:49], off

.Lstg_3:
	s_and_b64 vcc, exec, s[6:7]
	s_mov_b64 s[8:9], -1
	s_cbranch_vccnz .LBB0_307
	v_add_u32_e32 v48, 0xe0, v102
	v_max_i32_e32 v48, 0, v48
	v_min_i32_e32 v48, s88, v48
	v_mov_b32_e32 v49, v91
	v_lshlrev_b64 v[48:49], s87, v[48:49]
	v_lshl_add_u64 v[48:49], v[48:49], 0, s[22:23]
	s_and_b32 s8, s91, 0x1c000
	v_lshlrev_b64 v[48:49], 8, v[48:49]
	s_add_i32 s8, s55, s8
	v_lshl_add_u64 v[50:51], v[104:105], 0, v[48:49]
	s_mov_b32 m0, s8
	v_lshl_add_u64 v[48:49], v[106:107], 0, v[48:49]
	global_load_lds_dwordx4 v[50:51], off
	s_add_i32 m0, s8, 0x2000
	s_mov_b64 s[8:9], 0
	global_load_lds_dwordx4 v[48:49], off

; __device__ __forceinline__ unsigned cvt_pk_bf16(float lo, float hi) { unsigned r; asm volatile("v_cvt_pk_bf16_f32 %0, %1, %2" : "=v"(r) : "v"(lo), "v"(hi)); return r; }
; #define AT_WAITV(n) asm volatile("s_waitcnt vmcnt(" #n ")" ::: "memory")
; __device__ __forceinline__ void attn_passes(const Params& p, LAS unsigned char* lds) {
;     ...
;                 float pe[8], psum = 0.f;
; #pragma unroll
;                 for (int jj = 0; jj < 8; ++jj) { pe[jj] = __builtin_amdgcn_exp2f(sv[jj] - m); psum += pe[jj]; }
;                 lsum += psum;
;                 u32x4 pw; pw.x = cvt_pk_bf16(pe[0], pe[1]); pw.y = cvt_pk_bf16(pe[2], pe[3]); pw.z = cvt_pk_bf16(pe[4], pe[5]); pw.w = cvt_pk_bf16(pe[6], pe[7]);
;                 const bf16x8 pb = __builtin_bit_cast(bf16x8, pw);
;                 asm volatile("s_waitcnt lgkmcnt(0)" : "+v"(t0[0]), "+v"(t1[0]), "+v"(t0[1]), "+v"(t1[1]), "+v"(t0[2]), "+v"(t1[2]), "+v"(t0[3]), "+v"(t1[3]) :: "memory");
;                 asm volatile("" : "+v"(t0[4]), "+v"(t1[4]), "+v"(t0[5]), "+v"(t1[5]), "+v"(t0[6]), "+v"(t1[6]), "+v"(t0[7]), "+v"(t1[7]) :: "memory");
; #pragma unroll
;                 for (int c = 0; c < 8; ++c) {
;                     const bf16x8 va = (bf16x8){t0[c][0], t0[c][1], t0[c][2], t0[c][3], t1[c][0], t1[c][1], t1[c][2], t1[c][3]};
;                     o[c] = __builtin_amdgcn_mfma_f32_16x16x32_bf16(va, pb, o[c], 0, 0, 0); }
;                 if (j == 4) { if (n < 3) AT_WAITV(6); }
;                 else if (j >= 1 && n >= 1) { if (n < 3 || has_nxt) AT_WAITV(14); else AT_WAITV(4); }
;                 AT_BAR();
;             }
;             float lt = lsum; lt += __shfl_xor(lt, 16); lt += __shfl_xor(lt, 32);
; #pragma unroll
;             for (int c = 0; c < 8; c += 2) {
;                 unsigned ax = cvt_pk_bf16(o[c][0], o[c][1]), ay = cvt_pk_bf16(o[c][2], o[c][3]), bx = cvt_pk_bf16(o[c + 1][0], o[c + 1][1]), by = cvt_pk_bf16(o[c + 1][2], o[c + 1][3]);
;                 const auto rx = __builtin_amdgcn_permlane16_swap(ax, bx, false, false); const auto ry = __builtin_amdgcn_permlane16_swap(ay, by, false, false);
;                 u32x4 sw; sw.x = rx[0]; sw.y = ry[0]; sw.z = rx[1]; sw.w = ry[1];
;                 *(u32x4*)(ob_bh + tq * 2048 + 16 * (c + (g & 1)) + 8 * (g >> 1)) = sw; }
;             if (g == 0) { ml_bh[tq * 32] = m; ml_bh[tq * 32 + 1] = lt; }
.LBB0_314:
	s_nop 1
	v_add_f32_e32 v16, 0, v65
	v_add_f32_e32 v16, v66, v16
	v_add_f32_e32 v16, v67, v16
	v_add_f32_e32 v16, v68, v16
	v_add_f32_e32 v16, v69, v16
	v_add_f32_e32 v16, v70, v16
	v_add_f32_e32 v16, v71, v16
	v_add_f32_e32 v16, v72, v16
	v_add_f32_e32 v18, v64, v16
	v_mov_b32_e32 v19, v18
	v_lshlrev_b64 v[16:17], s87, v[90:91]
	v_lshl_add_u64 v[16:17], v[16:17], 0, s[22:23]
	s_barrier
	s_cmp_eq_u32 s101, 0
	s_cbranch_scc1 .Lstg_4
	s_sleep 11
.Lstg_4:
	v_lshlrev_b64 v[24:25], 12, v[16:17]
	v_cvt_pk_bf16_f32 v20, v44, v45
	v_cvt_pk_bf16_f32 v21, v46, v47
	v_cvt_pk_bf16_f32 v22, v40, v41
	v_cvt_pk_bf16_f32 v23, v42, v43
	v_lshl_add_u64 v[24:25], v[156:157], 0, v[24:25]
	v_permlane16_swap_b32_e32 v20, v22
	v_permlane16_swap_b32_e32 v21, v23
	v_permlane16_swap_b32_e32 v18, v19
	v_add_f32_e32 v18, v18, v19
	global_store_dwordx4 v[24:25], v[20:23], off sc1
	v_mov_b32_e32 v19, v18
	v_mov_b32_e32 v161, v18
	s_nop 0
	v_cvt_pk_bf16_f32 v20, v36, v37
	v_cvt_pk_bf16_f32 v21, v38, v39
	v_cvt_pk_bf16_f32 v22, v32, v33
	v_cvt_pk_bf16_f32 v23, v34, v35
	s_nop 0
	v_permlane16_swap_b32_e32 v20, v22
	v_permlane16_swap_b32_e32 v21, v23
	global_store_dwordx4 v[24:25], v[20:23], off offset:64 sc1
	v_cvt_pk_bf16_f32 v12, v12, v13
	v_cvt_pk_bf16_f32 v13, v14, v15
	v_cvt_pk_bf16_f32 v14, v8, v9
	v_cvt_pk_bf16_f32 v15, v10, v11
	s_nop 0
	v_permlane16_swap_b32_e32 v12, v14
	v_permlane16_swap_b32_e32 v13, v15
	global_store_dwordx4 v[24:25], v[12:15], off offset:128 sc1
	v_cvt_pk_bf16_f32 v4, v4, v5
	v_cvt_pk_bf16_f32 v5, v6, v7
	v_cvt_pk_bf16_f32 v6, v0, v1
	v_cvt_pk_bf16_f32 v7, v2, v3
	s_nop 0
	v_permlane16_swap_b32_e32 v4, v6
	v_permlane16_swap_b32_e32 v5, v7
	global_store_dwordx4 v[24:25], v[4:7], off offset:192 sc1
	v_permlane32_swap_b32_e32 v161, v19
	s_and_saveexec_b64 s[6:7], s[4:5]
	s_cbranch_execz .LBB0_256
	v_lshlrev_b64 v[0:1], 7, v[16:17]
	v_lshl_add_u64 v[0:1], s[48:49], 0, v[0:1]
	s_waitcnt lgkmcnt(0)
	v_add_f32_e32 v161, v18, v19
	global_store_dwordx2 v[0:1], v[160:161], off
	s_branch .LBB0_256
